# indexer: the 8 per-lane candidate appends batched (all 8 LDS atomic position fetches issued back to back under their lane masks, one counted wait each, then the 8 entry writes) instead of 8 serialized
# speedup vs baseline: 1.0222x; 1.0069x over previous
; __device__ __forceinline__ void lds_barrier() { asm volatile("s_waitcnt lgkmcnt(0)" ::: "memory"); __builtin_amdgcn_s_barrier(); asm volatile("" ::: "memory"); }
; __device__ __forceinline__ unsigned lds_add(LAS unsigned* p, unsigned v) { return __hip_atomic_fetch_add(p, v, __ATOMIC_RELAXED, __HIP_MEMORY_SCOPE_WORKGROUP); }
; __device__ __forceinline__ unsigned f2key(float x) { const unsigned u = __float_as_uint(x); return (u & 0x80000000u) ? ~u : (u | 0x80000000u); }
; __device__ void indexer_item(LAS unsigned char* lds, const bf16_t* Qi, const bf16_t* Ki, const float* Wi, unsigned* maskout, int qt) {
;     ...
;         unsigned k32[8]; int keyi[8];
; #pragma unroll
;         for (int j = 0; j < 4; ++j) { k32[j] = f2key(sc0[j]); k32[4 + j] = f2key(sc1[j]); keyi[j] = kb + quad * 4 + j; keyi[4 + j] = kb + 16 + quad * 4 + j; }
;         int np = 0;
; #pragma unroll
;         for (int j = 0; j < 8; ++j) np += (keyi[j] <= tq && k32[j] > thr) ? 1 : 0;
;         const int cnoff = (it & 1) ? 48 : 16;
;         if (np) lds_add(cnt + cnoff + q, (unsigned)np);
;         lds_barrier();
;         bool round;
;         {
;             const unsigned both = (lane < 16) ? cnt[lane] + cnt[cnoff + lane] : 0u;
;             if (tid < 16) cnt[(cnoff ^ 32) + tid] = 0u;
;             round = __ballot(both > 512u) != 0ull;
;             if (round) {
; #pragma unroll 1
;                 for (int qq = 0; qq < 2; ++qq) { const int qi = 2 * wid + qq; const unsigned cc = cnt[qi], cn = cnt[cnoff + qi];
;                     if (cc + cn > 512u || cc > 320u) {
;                         if (cn > 192u || cc <= 320u) select256<true>(lds, qi, wid, lane); else select256<false>(lds, qi, wid, lane); } }
;             }
;         }
;         lds_barrier();
;         if (round) thr = cnt[32 + q];
; #pragma unroll
;         for (int j = 0; j < 8; ++j) if (keyi[j] <= tq && k32[j] > thr) {
;             const unsigned pos = lds_add(cnt + q, 1u);
;             if (pos < 512u) cand[q * 512 + pos] = ((u64)k32[j] << 16) | (u64)(16383 - keyi[j]);
;         }
.LBB0_728:
	s_waitcnt lgkmcnt(0)
	v_cmp_gt_u32_e32 vcc, v154, v101
	s_and_b64 s[24:25], s[24:25], vcc
	v_cmp_gt_u32_e32 vcc, v44, v101
	s_and_b64 s[22:23], s[22:23], vcc
	v_cmp_gt_u32_e32 vcc, v42, v101
	s_and_b64 s[20:21], s[20:21], vcc
	v_cmp_gt_u32_e32 vcc, v40, v101
	s_and_b64 s[18:19], s[18:19], vcc
	v_cmp_gt_u32_e32 vcc, v38, v101
	s_and_b64 s[16:17], s[16:17], vcc
	v_cmp_gt_u32_e32 vcc, v36, v101
	s_and_b64 s[14:15], s[14:15], vcc
	v_cmp_gt_u32_e32 vcc, v34, v101
	s_and_b64 s[12:13], s[12:13], vcc
	v_cmp_gt_u32_e32 vcc, v32, v101
	s_and_b64 s[10:11], s[10:11], vcc
	s_or_b64 vcc, s[24:25], s[22:23]
	s_or_b64 vcc, vcc, s[20:21]
	s_or_b64 vcc, vcc, s[18:19]
	s_or_b64 vcc, vcc, s[16:17]
	s_or_b64 vcc, vcc, s[14:15]
	s_or_b64 vcc, vcc, s[12:13]
	s_or_b64 vcc, vcc, s[10:11]
	s_cbranch_scc0 .Lix_noapp
	s_mov_b64 s[26:27], exec
	s_mov_b64 exec, s[24:25]
	ds_add_rtn_u32 v240, v81, v180
	s_mov_b64 exec, s[22:23]
	ds_add_rtn_u32 v241, v81, v180
	s_mov_b64 exec, s[20:21]
	ds_add_rtn_u32 v242, v81, v180
	s_mov_b64 exec, s[18:19]
	ds_add_rtn_u32 v243, v81, v180
	s_mov_b64 exec, s[16:17]
	ds_add_rtn_u32 v244, v81, v180
	s_mov_b64 exec, s[14:15]
	ds_add_rtn_u32 v245, v81, v180
	s_mov_b64 exec, s[12:13]
	ds_add_rtn_u32 v246, v81, v180
	s_mov_b64 exec, s[10:11]
	ds_add_rtn_u32 v247, v81, v180
	s_mov_b64 exec, s[26:27]
	v_sub_u32_e32 v33, 0x3fff, v43
	v_lshl_or_b32 v248, v154, 16, v33
	v_ashrrev_i32_e32 v33, 31, v33
	v_lshrrev_b32_e32 v249, 16, v154
	v_or_b32_e32 v249, v249, v33
	v_sub_u32_e32 v33, 0x3ffe, v43
	v_lshl_or_b32 v250, v44, 16, v33
	v_ashrrev_i32_e32 v33, 31, v33
	v_lshrrev_b32_e32 v251, 16, v44
	v_or_b32_e32 v251, v251, v33
	v_sub_u32_e32 v33, 0x3fff, v41
	v_lshl_or_b32 v252, v42, 16, v33
	v_ashrrev_i32_e32 v33, 31, v33
	v_lshrrev_b32_e32 v253, 16, v42
	v_or_b32_e32 v253, v253, v33
	v_sub_u32_e32 v33, 0x3fff, v107
	v_lshl_or_b32 v254, v40, 16, v33
	v_ashrrev_i32_e32 v33, 31, v33
	v_lshrrev_b32_e32 v255, 16, v40
	v_or_b32_e32 v255, v255, v33
	v_sub_u32_e32 v33, 0x3fff, v106
	v_lshl_or_b32 v46, v38, 16, v33
	v_ashrrev_i32_e32 v33, 31, v33
	v_lshrrev_b32_e32 v47, 16, v38
	v_or_b32_e32 v47, v47, v33
	v_sub_u32_e32 v33, 0x3fff, v35
	v_lshl_or_b32 v44, v36, 16, v33
	v_ashrrev_i32_e32 v33, 31, v33
	v_lshrrev_b32_e32 v45, 16, v36
	v_or_b32_e32 v45, v45, v33
	v_sub_u32_e32 v33, 0x3fff, v105
	v_lshl_or_b32 v42, v34, 16, v33
	v_ashrrev_i32_e32 v33, 31, v33
	v_lshrrev_b32_e32 v43, 16, v34
	v_or_b32_e32 v43, v43, v33
	v_sub_u32_e32 v33, 0x3fff, v104
	v_lshl_or_b32 v40, v32, 16, v33
	v_ashrrev_i32_e32 v33, 31, v33
	v_lshrrev_b32_e32 v41, 16, v32
	v_or_b32_e32 v41, v41, v33
	s_waitcnt lgkmcnt(7)
	s_mov_b64 exec, s[24:25]
	v_cmp_gt_u32_e32 vcc, s73, v240
	s_and_b64 exec, exec, vcc
	v_lshl_add_u32 v240, v240, 3, v102
	ds_write_b64 v240, v[248:249] offset:35072
	s_waitcnt lgkmcnt(7)
	s_mov_b64 exec, s[22:23]
	v_cmp_gt_u32_e32 vcc, s73, v241
	s_and_b64 exec, exec, vcc
	v_lshl_add_u32 v241, v241, 3, v102
	ds_write_b64 v241, v[250:251] offset:35072
	s_waitcnt lgkmcnt(7)
	s_mov_b64 exec, s[20:21]
	v_cmp_gt_u32_e32 vcc, s73, v242
	s_and_b64 exec, exec, vcc
	v_lshl_add_u32 v242, v242, 3, v102
	ds_write_b64 v242, v[252:253] offset:35072
	s_waitcnt lgkmcnt(7)
	s_mov_b64 exec, s[18:19]
	v_cmp_gt_u32_e32 vcc, s73, v243
	s_and_b64 exec, exec, vcc
	v_lshl_add_u32 v243, v243, 3, v102
	ds_write_b64 v243, v[254:255] offset:35072
	s_waitcnt lgkmcnt(7)
	s_mov_b64 exec, s[16:17]
	v_cmp_gt_u32_e32 vcc, s73, v244
	s_and_b64 exec, exec, vcc
	v_lshl_add_u32 v244, v244, 3, v102
	ds_write_b64 v244, v[46:47] offset:35072
	s_waitcnt lgkmcnt(7)
	s_mov_b64 exec, s[14:15]
	v_cmp_gt_u32_e32 vcc, s73, v245
	s_and_b64 exec, exec, vcc
	v_lshl_add_u32 v245, v245, 3, v102
	ds_write_b64 v245, v[44:45] offset:35072
	s_waitcnt lgkmcnt(7)
	s_mov_b64 exec, s[12:13]
	v_cmp_gt_u32_e32 vcc, s73, v246
	s_and_b64 exec, exec, vcc
	v_lshl_add_u32 v246, v246, 3, v102
	ds_write_b64 v246, v[42:43] offset:35072
	s_waitcnt lgkmcnt(7)
	s_mov_b64 exec, s[10:11]
	v_cmp_gt_u32_e32 vcc, s73, v247
	s_and_b64 exec, exec, vcc
	v_lshl_add_u32 v247, v247, 3, v102
	ds_write_b64 v247, v[40:41] offset:35072
	s_mov_b64 exec, s[26:27]
.Lix_noapp:
	s_branch .LBB0_635
.LBB0_752:
	v_mov_b32_e32 v48, v74
	v_mov_b32_e32 v49, v75
	v_mov_b32_e32 v50, v76
	v_mov_b32_e32 v51, v77
	v_mov_b32_e32 v52, v78
	v_mov_b32_e32 v53, v79
	v_mov_b32_e32 v54, v80
